# norm phase: x rows loaded with nt (streamed, keeps hx resident in the cache hierarchy for inproj)
# speedup vs baseline: 1.0132x; 1.0073x over previous
; DI u32x2 pack4(f32x4 v) { u32x2 r = {cvtpk(v[0], v[1]), cvtpk(v[2], v[3])}; return r; }
; DI float red64(float v) { v = red16(v); v += __shfl_xor(v, 16); v += __shfl_xor(v, 32); return v; }
; DI void phase_norm(KP p, int l) {
;     ...
;     f32x4 v[4]; float ss = 0.f;
; #pragma unroll
;     for (int i = 0; i < 4; ++i) { v[i] = *(const f32x4*)(src + i * 256 + lane * 4); ss += v[i][0] * v[i][0] + v[i][1] * v[i][1] + v[i][2] * v[i][2] + v[i][3] * v[i][3]; }
;     ss = red64(ss);
;     const float rstd = rsqrtf(ss * (1.f / 1024.f) + 1e-6f);
; #pragma unroll
;     for (int i = 0; i < 4; ++i) {
;       const int k = i * 256 + lane * 4;
;       f32x4 o;
; #pragma unroll
;       for (int e = 0; e < 4; ++e) o[e] = v[i][e] * rstd * G[i][e] + SH[i][e];
;       *(u32x2*)(hx + (size_t)r * 1024 + k) = pack4(o);
;     }
.LBB0_274:
	s_or_b64 exec, exec, s[18:19]
	v_lshl_add_u64 v[52:53], v[48:49], 0, v[0:1]
	global_load_dwordx4 v[48:51], v[52:53], off nt
	global_load_dwordx4 v[56:59], v[52:53], off offset:1024 nt
	global_load_dwordx4 v[60:63], v[52:53], off offset:2048 nt
	global_load_dwordx4 v[64:67], v[52:53], off offset:3072 nt
	s_mov_b32 s2, 0x800000
	s_waitcnt vmcnt(0) lgkmcnt(0)
	v_mov_b32_e32 v68, v49
	v_mov_b32_e32 v69, v57
	v_mov_b32_e32 v52, v48
	v_mov_b32_e32 v53, v56
	v_mov_b32_e32 v76, v61
	v_mov_b32_e32 v77, v65
	v_pk_mul_f32 v[68:69], v[68:69], v[68:69]
	v_mov_b32_e32 v70, v50
	v_mov_b32_e32 v71, v58
	v_mov_b32_e32 v74, v60
	v_mov_b32_e32 v75, v64
	v_pk_mul_f32 v[76:77], v[76:77], v[76:77]
	v_pk_fma_f32 v[52:53], v[52:53], v[52:53], v[68:69]
	v_mov_b32_e32 v72, v51
	v_mov_b32_e32 v73, v59
	v_mov_b32_e32 v78, v62
	v_mov_b32_e32 v79, v66
	v_pk_fma_f32 v[68:69], v[74:75], v[74:75], v[76:77]
	v_pk_fma_f32 v[52:53], v[70:71], v[70:71], v[52:53]
	v_mov_b32_e32 v80, v63
	v_mov_b32_e32 v81, v67
	v_pk_fma_f32 v[68:69], v[78:79], v[78:79], v[68:69]
	v_pk_fma_f32 v[52:53], v[72:73], v[72:73], v[52:53]
	v_pk_fma_f32 v[68:69], v[80:81], v[80:81], v[68:69]
	v_add_f32_e32 v0, v52, v53
	v_add_f32_e32 v0, v0, v68
	v_add_f32_e32 v0, v0, v69
	s_nop 1
	v_add_f32_dpp v0, v0, v0 quad_perm:[1,0,3,2] row_mask:0xf bank_mask:0xf bound_ctrl:1
	s_nop 1
	v_add_f32_dpp v0, v0, v0 quad_perm:[2,3,0,1] row_mask:0xf bank_mask:0xf bound_ctrl:1
	s_nop 1
	v_add_f32_dpp v0, v0, v0 row_ror:4 row_mask:0xf bank_mask:0xf bound_ctrl:1
	s_nop 1
	v_add_f32_dpp v0, v0, v0 row_ror:8 row_mask:0xf bank_mask:0xf bound_ctrl:1
	ds_bpermute_b32 v35, v54, v0
	s_waitcnt lgkmcnt(0)
	v_add_f32_e32 v0, v0, v35
	ds_bpermute_b32 v45, v55, v0
	v_ashrrev_i32_e32 v35, 31, v34
	v_lshlrev_b64 v[52:53], 11, v[34:35]
	v_add_u32_e32 v34, 1, v34
	v_cmp_ge_i32_e64 s[40:41], v34, v37
	s_waitcnt lgkmcnt(0)
	v_add_f32_e32 v0, v0, v45
	v_fmamk_f32 v0, v0, 0x3a800000, v198
	v_mul_f32_e32 v35, 0x4b800000, v0
	v_cmp_gt_f32_e32 vcc, s2, v0
	v_lshl_add_u64 v[52:53], v[40:41], 0, v[52:53]
	s_or_b64 s[46:47], s[40:41], s[46:47]
	v_cndmask_b32_e32 v0, v0, v35, vcc
	v_rsq_f32_e32 v0, v0
	s_nop 0
	v_mul_f32_e32 v35, 0x45800000, v0
	v_cndmask_b32_e32 v0, v0, v35, vcc
	v_pk_mul_f32 v[48:49], v[48:49], v[0:1] op_sel_hi:[1,0]
	v_pk_mul_f32 v[50:51], v[50:51], v[0:1] op_sel_hi:[1,0]
	v_pk_mul_f32 v[56:57], v[56:57], v[0:1] op_sel_hi:[1,0]
	v_pk_mul_f32 v[58:59], v[58:59], v[0:1] op_sel_hi:[1,0]
	v_pk_mul_f32 v[60:61], v[60:61], v[0:1] op_sel_hi:[1,0]
	v_pk_mul_f32 v[62:63], v[62:63], v[0:1] op_sel_hi:[1,0]
	v_pk_mul_f32 v[64:65], v[64:65], v[0:1] op_sel_hi:[1,0]
	v_pk_mul_f32 v[66:67], v[66:67], v[0:1] op_sel_hi:[1,0]
	v_pk_fma_f32 v[48:49], v[2:3], v[48:49], v[30:31]
	v_pk_fma_f32 v[50:51], v[4:5], v[50:51], v[32:33]
	v_pk_fma_f32 v[56:57], v[6:7], v[56:57], v[26:27]
	v_pk_fma_f32 v[58:59], v[8:9], v[58:59], v[28:29]
	v_pk_fma_f32 v[60:61], v[10:11], v[60:61], v[22:23]
	v_pk_fma_f32 v[62:63], v[12:13], v[62:63], v[24:25]
	v_pk_fma_f32 v[64:65], v[14:15], v[64:65], v[18:19]
	v_pk_fma_f32 v[66:67], v[16:17], v[66:67], v[20:21]
	v_cvt_pk_bf16_f32 v48, v48, v49
	v_cvt_pk_bf16_f32 v49, v50, v51
	v_cvt_pk_bf16_f32 v50, v56, v57
	v_cvt_pk_bf16_f32 v51, v58, v59
	v_cvt_pk_bf16_f32 v56, v60, v61
	v_cvt_pk_bf16_f32 v57, v62, v63
	v_cvt_pk_bf16_f32 v58, v64, v65
	v_cvt_pk_bf16_f32 v59, v66, v67
	global_store_dwordx2 v[52:53], v[48:49], off
	global_store_dwordx2 v[52:53], v[50:51], off offset:512
	global_store_dwordx2 v[52:53], v[56:57], off offset:1024
	global_store_dwordx2 v[52:53], v[58:59], off offset:1536
	s_andn2_b64 exec, exec, s[46:47]
	s_cbranch_execz .LBB0_283
